# de-serialized the HGRN chunk scan (64 loads up front, counted waits) and hoisted the pool-GEMM epilogue pool_scale loads
# baseline (speedup 1.0000x reference)
; DEVI int tidx() { int t = threadIdx.x; asm volatile("" : "+v"(t)); return t; }
; DEVI void run_phase(const Params& p, int ph, char* smem) {
;     ...
;         for (int e = blockIdx.x * 256 + tidx(); e < 8 * 4 * 4096; e += G * 256) {
;           const int b = e >> 14, h = (e >> 12) & 3, kv = e & 4095, k = kv >> 6;
;           float S = 0.f;
; #pragma unroll
;           for (int c = 0; c < 32; c++) {
;             const size_t o = (size_t)(b * 32 + c) * 4 + h;
;             hS[o * 4096 + kv] = S;
;             S = hD[o * 64 + k] * S + hU[o * 4096 + kv];
;           }
;           p.out[O_HGRN_P + (((size_t)l * 8 + b) * 4 + h) * 4096 + kv] = S;
;         }
.LBB0_873:
	v_ashrrev_i32_e32 v2, 14, v8
	v_bfe_u32 v9, v8, 12, 2
	v_lshrrev_b32_e32 v0, 4, v8
	v_and_b32_e32 v0, 0xfc, v0
	v_lshlrev_b32_e32 v10, 2, v8
	v_and_b32_e32 v10, 0x3ffc, v10
	v_lshlrev_b32_e32 v6, 7, v2
	v_or_b32_e32 v6, v6, v9
	v_lshl_or_b32 v11, v6, 14, v10
	v_lshl_or_b32 v12, v6, 8, v0
	v_mov_b32_e32 v14, v11
	v_add_u32_e32 v8, s36, v8
	s_mov_b32 s3, 0x1ffff
	global_load_dword v20, v12, s[14:15]
	global_load_dword v52, v11, s[12:13]
	v_add_u32_e32 v12, 0x400, v12
	v_add_u32_e32 v11, 0x10000, v11
	global_load_dword v21, v12, s[14:15]
	global_load_dword v53, v11, s[12:13]
	v_add_u32_e32 v12, 0x400, v12
	v_add_u32_e32 v11, 0x10000, v11
	global_load_dword v22, v12, s[14:15]
	global_load_dword v54, v11, s[12:13]
	v_add_u32_e32 v12, 0x400, v12
	v_add_u32_e32 v11, 0x10000, v11
	global_load_dword v23, v12, s[14:15]
	global_load_dword v55, v11, s[12:13]
	v_add_u32_e32 v12, 0x400, v12
	v_add_u32_e32 v11, 0x10000, v11
	global_load_dword v24, v12, s[14:15]
	global_load_dword v56, v11, s[12:13]
	v_add_u32_e32 v12, 0x400, v12
	v_add_u32_e32 v11, 0x10000, v11
	global_load_dword v25, v12, s[14:15]
	global_load_dword v57, v11, s[12:13]
	v_add_u32_e32 v12, 0x400, v12
	v_add_u32_e32 v11, 0x10000, v11
	global_load_dword v26, v12, s[14:15]
	global_load_dword v58, v11, s[12:13]
	v_add_u32_e32 v12, 0x400, v12
	v_add_u32_e32 v11, 0x10000, v11
	global_load_dword v27, v12, s[14:15]
	global_load_dword v59, v11, s[12:13]
	v_add_u32_e32 v12, 0x400, v12
	v_add_u32_e32 v11, 0x10000, v11
	global_load_dword v28, v12, s[14:15]
	global_load_dword v60, v11, s[12:13]
	v_add_u32_e32 v12, 0x400, v12
	v_add_u32_e32 v11, 0x10000, v11
	global_load_dword v29, v12, s[14:15]
	global_load_dword v61, v11, s[12:13]
	v_add_u32_e32 v12, 0x400, v12
	v_add_u32_e32 v11, 0x10000, v11
	global_load_dword v30, v12, s[14:15]
	global_load_dword v62, v11, s[12:13]
	v_add_u32_e32 v12, 0x400, v12
	v_add_u32_e32 v11, 0x10000, v11
	global_load_dword v31, v12, s[14:15]
	global_load_dword v63, v11, s[12:13]
	v_add_u32_e32 v12, 0x400, v12
	v_add_u32_e32 v11, 0x10000, v11
	global_load_dword v32, v12, s[14:15]
	global_load_dword v64, v11, s[12:13]
	v_add_u32_e32 v12, 0x400, v12
	v_add_u32_e32 v11, 0x10000, v11
	global_load_dword v33, v12, s[14:15]
	global_load_dword v65, v11, s[12:13]
	v_add_u32_e32 v12, 0x400, v12
	v_add_u32_e32 v11, 0x10000, v11
	global_load_dword v34, v12, s[14:15]
	global_load_dword v66, v11, s[12:13]
	v_add_u32_e32 v12, 0x400, v12
	v_add_u32_e32 v11, 0x10000, v11
	global_load_dword v35, v12, s[14:15]
	global_load_dword v67, v11, s[12:13]
	v_add_u32_e32 v12, 0x400, v12
	v_add_u32_e32 v11, 0x10000, v11
	global_load_dword v36, v12, s[14:15]
	global_load_dword v68, v11, s[12:13]
	v_add_u32_e32 v12, 0x400, v12
	v_add_u32_e32 v11, 0x10000, v11
	global_load_dword v37, v12, s[14:15]
	global_load_dword v69, v11, s[12:13]
	v_add_u32_e32 v12, 0x400, v12
	v_add_u32_e32 v11, 0x10000, v11
	global_load_dword v38, v12, s[14:15]
	global_load_dword v70, v11, s[12:13]
	v_add_u32_e32 v12, 0x400, v12
	v_add_u32_e32 v11, 0x10000, v11
	global_load_dword v39, v12, s[14:15]
	global_load_dword v71, v11, s[12:13]
	v_add_u32_e32 v12, 0x400, v12
	v_add_u32_e32 v11, 0x10000, v11
	global_load_dword v40, v12, s[14:15]
	global_load_dword v72, v11, s[12:13]
	v_add_u32_e32 v12, 0x400, v12
	v_add_u32_e32 v11, 0x10000, v11
	global_load_dword v41, v12, s[14:15]
	global_load_dword v73, v11, s[12:13]
	v_add_u32_e32 v12, 0x400, v12
	v_add_u32_e32 v11, 0x10000, v11
	global_load_dword v42, v12, s[14:15]
	global_load_dword v74, v11, s[12:13]
	v_add_u32_e32 v12, 0x400, v12
	v_add_u32_e32 v11, 0x10000, v11
	global_load_dword v43, v12, s[14:15]
	global_load_dword v75, v11, s[12:13]
	v_add_u32_e32 v12, 0x400, v12
	v_add_u32_e32 v11, 0x10000, v11
	global_load_dword v44, v12, s[14:15]
	global_load_dword v76, v11, s[12:13]
	v_add_u32_e32 v12, 0x400, v12
	v_add_u32_e32 v11, 0x10000, v11
	global_load_dword v45, v12, s[14:15]
	global_load_dword v77, v11, s[12:13]
	v_add_u32_e32 v12, 0x400, v12
	v_add_u32_e32 v11, 0x10000, v11
	global_load_dword v46, v12, s[14:15]
	global_load_dword v78, v11, s[12:13]
	v_add_u32_e32 v12, 0x400, v12
	v_add_u32_e32 v11, 0x10000, v11
	global_load_dword v47, v12, s[14:15]
	global_load_dword v79, v11, s[12:13]
	v_add_u32_e32 v12, 0x400, v12
	v_add_u32_e32 v11, 0x10000, v11
	global_load_dword v48, v12, s[14:15]
	global_load_dword v80, v11, s[12:13]
	v_add_u32_e32 v12, 0x400, v12
	v_add_u32_e32 v11, 0x10000, v11
	global_load_dword v49, v12, s[14:15]
	global_load_dword v81, v11, s[12:13]
	v_add_u32_e32 v12, 0x400, v12
	v_add_u32_e32 v11, 0x10000, v11
	global_load_dword v50, v12, s[14:15]
	global_load_dword v82, v11, s[12:13]
	v_add_u32_e32 v12, 0x400, v12
	v_add_u32_e32 v11, 0x10000, v11
	global_load_dword v51, v12, s[14:15]
	global_load_dword v83, v11, s[12:13]
	v_mov_b32_e32 v16, 0
	global_store_dword v14, v16, s[8:9]
	s_waitcnt vmcnt(63)
; DEVI void run_phase(const Params& p, int ph, char* smem) {
;     ...
; #pragma unroll
;           for (int c = 0; c < 32; c++) {
;             const size_t o = (size_t)(b * 32 + c) * 4 + h;
;             hS[o * 4096 + kv] = S;
;             S = hD[o * 64 + k] * S + hU[o * 4096 + kv];
;           }
;           p.out[O_HGRN_P + (((size_t)l * 8 + b) * 4 + h) * 4096 + kv] = S;
	v_fma_f32 v16, v20, v16, v52
	v_add_u32_e32 v14, 0x10000, v14
	global_store_dword v14, v16, s[8:9]
	s_waitcnt vmcnt(62)
	v_fma_f32 v16, v21, v16, v53
	v_add_u32_e32 v14, 0x10000, v14
	global_store_dword v14, v16, s[8:9]
	s_waitcnt vmcnt(61)
	v_fma_f32 v16, v22, v16, v54
	v_add_u32_e32 v14, 0x10000, v14
	global_store_dword v14, v16, s[8:9]
	s_waitcnt vmcnt(60)
	v_fma_f32 v16, v23, v16, v55
	v_add_u32_e32 v14, 0x10000, v14
	global_store_dword v14, v16, s[8:9]
	s_waitcnt vmcnt(59)
	v_fma_f32 v16, v24, v16, v56
	v_add_u32_e32 v14, 0x10000, v14
	global_store_dword v14, v16, s[8:9]
	s_waitcnt vmcnt(58)
	v_fma_f32 v16, v25, v16, v57
	v_add_u32_e32 v14, 0x10000, v14
	global_store_dword v14, v16, s[8:9]
	s_waitcnt vmcnt(57)
	v_fma_f32 v16, v26, v16, v58
	v_add_u32_e32 v14, 0x10000, v14
	global_store_dword v14, v16, s[8:9]
	s_waitcnt vmcnt(56)
	v_fma_f32 v16, v27, v16, v59
	v_add_u32_e32 v14, 0x10000, v14
	global_store_dword v14, v16, s[8:9]
	s_waitcnt vmcnt(55)
	v_fma_f32 v16, v28, v16, v60
	v_add_u32_e32 v14, 0x10000, v14
	global_store_dword v14, v16, s[8:9]
	s_waitcnt vmcnt(54)
	v_fma_f32 v16, v29, v16, v61
	v_add_u32_e32 v14, 0x10000, v14
	global_store_dword v14, v16, s[8:9]
	s_waitcnt vmcnt(53)
	v_fma_f32 v16, v30, v16, v62
	v_add_u32_e32 v14, 0x10000, v14
	global_store_dword v14, v16, s[8:9]
	s_waitcnt vmcnt(52)
	v_fma_f32 v16, v31, v16, v63
	v_add_u32_e32 v14, 0x10000, v14
	global_store_dword v14, v16, s[8:9]
	s_waitcnt vmcnt(51)
	v_fma_f32 v16, v32, v16, v64
	v_add_u32_e32 v14, 0x10000, v14
	global_store_dword v14, v16, s[8:9]
	s_waitcnt vmcnt(50)
	v_fma_f32 v16, v33, v16, v65
	v_add_u32_e32 v14, 0x10000, v14
	global_store_dword v14, v16, s[8:9]
	s_waitcnt vmcnt(49)
	v_fma_f32 v16, v34, v16, v66
	v_add_u32_e32 v14, 0x10000, v14
	global_store_dword v14, v16, s[8:9]
	s_waitcnt vmcnt(48)
	v_fma_f32 v16, v35, v16, v67
	v_add_u32_e32 v14, 0x10000, v14
	global_store_dword v14, v16, s[8:9]
	s_waitcnt vmcnt(47)
	v_fma_f32 v16, v36, v16, v68
	v_add_u32_e32 v14, 0x10000, v14
	global_store_dword v14, v16, s[8:9]
	s_waitcnt vmcnt(46)
	v_fma_f32 v16, v37, v16, v69
	v_add_u32_e32 v14, 0x10000, v14
	global_store_dword v14, v16, s[8:9]
	s_waitcnt vmcnt(45)
	v_fma_f32 v16, v38, v16, v70
	v_add_u32_e32 v14, 0x10000, v14
	global_store_dword v14, v16, s[8:9]
	s_waitcnt vmcnt(44)
	v_fma_f32 v16, v39, v16, v71
	v_add_u32_e32 v14, 0x10000, v14
	global_store_dword v14, v16, s[8:9]
	s_waitcnt vmcnt(43)
	v_fma_f32 v16, v40, v16, v72
	v_add_u32_e32 v14, 0x10000, v14
	global_store_dword v14, v16, s[8:9]
	s_waitcnt vmcnt(42)
	v_fma_f32 v16, v41, v16, v73
	v_add_u32_e32 v14, 0x10000, v14
	global_store_dword v14, v16, s[8:9]
	s_waitcnt vmcnt(41)
	v_fma_f32 v16, v42, v16, v74
	v_add_u32_e32 v14, 0x10000, v14
	global_store_dword v14, v16, s[8:9]
	s_waitcnt vmcnt(40)
	v_fma_f32 v16, v43, v16, v75
	v_add_u32_e32 v14, 0x10000, v14
	global_store_dword v14, v16, s[8:9]
	s_waitcnt vmcnt(39)
	v_fma_f32 v16, v44, v16, v76
	v_add_u32_e32 v14, 0x10000, v14
	global_store_dword v14, v16, s[8:9]
	s_waitcnt vmcnt(38)
	v_fma_f32 v16, v45, v16, v77
	v_add_u32_e32 v14, 0x10000, v14
	global_store_dword v14, v16, s[8:9]
	s_waitcnt vmcnt(37)
	v_fma_f32 v16, v46, v16, v78
	v_add_u32_e32 v14, 0x10000, v14
	global_store_dword v14, v16, s[8:9]
	s_waitcnt vmcnt(36)
	v_fma_f32 v16, v47, v16, v79
	v_add_u32_e32 v14, 0x10000, v14
	global_store_dword v14, v16, s[8:9]
	s_waitcnt vmcnt(35)
	v_fma_f32 v16, v48, v16, v80
	v_add_u32_e32 v14, 0x10000, v14
	global_store_dword v14, v16, s[8:9]
	s_waitcnt vmcnt(34)
	v_fma_f32 v16, v49, v16, v81
	v_add_u32_e32 v14, 0x10000, v14
	global_store_dword v14, v16, s[8:9]
	s_waitcnt vmcnt(33)
	v_fma_f32 v16, v50, v16, v82
	v_add_u32_e32 v14, 0x10000, v14
	global_store_dword v14, v16, s[8:9]
	s_waitcnt vmcnt(32)
	v_fma_f32 v16, v51, v16, v83
	v_ashrrev_i32_e32 v3, 31, v2
	v_lshl_add_u64 v[2:3], v[2:3], 2, s[0:1]
	v_or_b32_e32 v2, v2, v9
	v_lshlrev_b64 v[2:3], 14, v[2:3]
	v_lshl_add_u64 v[2:3], s[10:11], 0, v[2:3]
	v_mov_b32_e32 v11, 0
	v_lshl_add_u64 v[2:3], v[2:3], 0, v[10:11]
	v_add_co_u32_e32 v2, vcc, 0x4600000, v2
	s_nop 1
	v_addc_co_u32_e32 v3, vcc, 0, v3, vcc
	v_cmp_lt_i32_e32 vcc, s3, v8
	s_or_b64 s[6:7], vcc, s[6:7]
	global_store_dword v[2:3], v16, off
	s_andn2_b64 exec, exec, s[6:7]
	s_cbranch_execnz .LBB0_873

; #define LAS __attribute__((address_space(3)))
;     ...
;   const int nk = (nk_part < 0) ? (K >> 5) : nk_part;
;   const int lrow = tid >> 2, lpc = tid & 3;
;   const int lch = lpc ^ ((0x78 >> (((lrow >> 2) & 3) * 2)) & 3);
;   const u16* ga = A + (size_t)(m0 + lrow) * lda + kbeg + lch * 8;
;   const u16* gb = Bt + (size_t)(n0 + lrow) * K + kbeg + lch * 8;
;   const size_t ga1 = (size_t)64 * lda, gb1 = (size_t)64 * K;
;   const unsigned lds0 = (unsigned)(uintptr_t)(LAS char*)smem + (unsigned)__builtin_amdgcn_readfirstlane(wid) * 1024u;
;     ...
;   __syncthreads();
;   GEMM_STAGE(0); GEMM_STAGE(1); GEMM_STAGE(2); GEMM_STAGE(3);
;   const int fsw = (0x78 >> (((r16 >> 2) & 3) * 2)) & 3;
;   const int aoff = (wm * 64 + r16) * 64 + ((quad ^ fsw) << 4);
;   const int boff = 8192 + (wn * 64 + r16) * 64 + ((quad ^ fsw) << 4);
;   bf16x8 xa0[4], wb0[4], xa1[4], wb1[4];
;     ...
;   asm volatile("s_waitcnt vmcnt(12)" ::: "memory");
;   __builtin_amdgcn_s_barrier();
;   asm volatile("" ::: "memory");
;   GEMM_READ(0, xa0, wb0);
.LBB0_876:
	v_mov_b32_e32 v62, v145
	s_lshl_b32 s3, s9, 7
	v_lshrrev_b32_e32 v0, 3, v62
	v_ashrrev_i32_e32 v4, 2, v62
	v_and_b32_e32 v0, 6, v0
	s_movk_i32 s46, 0x78
	v_lshrrev_b32_e64 v0, v0, s46
	v_add_u32_e32 v2, s3, v4
	s_lshl_b32 s2, s8, 7
	v_xor_b32_e32 v0, v0, v62
	v_ashrrev_i32_e32 v3, 31, v2
	v_readlane_b32 s8, v251, 36
	v_lshlrev_b64 v[2:3], 9, v[2:3]
	v_readlane_b32 s9, v251, 37
	v_lshlrev_b32_e32 v0, 4, v0
	v_and_b32_e32 v0, 48, v0
	v_lshl_add_u64 v[2:3], s[8:9], 0, v[2:3]
	s_waitcnt vmcnt(0)
	v_lshl_add_u64 v[58:59], v[2:3], 0, v[0:1]
	v_add_u32_e32 v2, s2, v4
	v_ashrrev_i32_e32 v3, 31, v2
	v_readfirstlane_b32 s8, v62
	v_lshlrev_b64 v[2:3], 9, v[2:3]
	s_lshl_b32 s8, s8, 4
	v_lshl_add_u64 v[2:3], s[4:5], 0, v[2:3]
	s_and_b32 s41, s8, 0xfffffc00
	s_barrier
	s_mov_b32 s8, m0
	s_mov_b32 m0, s41
	s_nop 0
	global_load_lds_dwordx4 v[58:59], off
	s_mov_b32 m0, s8
	s_mov_b64 s[10:11], 0x8000
	v_lshl_add_u64 v[60:61], v[2:3], 0, v[0:1]
	v_lshl_add_u64 v[2:3], v[58:59], 0, s[10:11]
	s_add_i32 s42, s41, 0x1000
	s_mov_b32 s8, m0
	s_mov_b32 m0, s42
	s_nop 0
	global_load_lds_dwordx4 v[2:3], off
	s_mov_b32 m0, s8
	s_add_i32 s43, s41, 0x2000
	s_mov_b32 s8, m0
	s_mov_b32 m0, s43
	s_nop 0
	global_load_lds_dwordx4 v[60:61], off
	s_mov_b32 m0, s8
	v_lshl_add_u64 v[2:3], v[60:61], 0, s[10:11]
	s_add_i32 s44, s41, 0x3000
	s_mov_b32 s8, m0
	s_mov_b32 m0, s44
	s_nop 0
	global_load_lds_dwordx4 v[2:3], off
	s_mov_b32 m0, s8
	s_add_i32 s36, s41, 0x4000
	v_lshl_add_u64 v[2:3], v[58:59], 0, 64
	s_mov_b32 s8, m0
	s_mov_b32 m0, s36
	s_nop 0
	global_load_lds_dwordx4 v[2:3], off
	s_mov_b32 m0, s8
	s_mov_b64 s[10:11], 0x8040
	v_lshl_add_u64 v[2:3], v[58:59], 0, s[10:11]
	s_add_i32 s37, s41, 0x5000
	s_mov_b32 s8, m0
	s_mov_b32 m0, s37
	s_nop 0
	global_load_lds_dwordx4 v[2:3], off
	s_mov_b32 m0, s8
	v_lshl_add_u64 v[4:5], v[60:61], 0, 64
	s_add_i32 s39, s41, 0x6000
	s_mov_b32 s8, m0
	s_mov_b32 m0, s39
	s_nop 0
	global_load_lds_dwordx4 v[4:5], off
	s_mov_b32 m0, s8
	v_lshl_add_u64 v[2:3], v[60:61], 0, s[10:11]
	s_add_i32 s40, s41, 0x7000
	s_mov_b32 s8, m0
	s_mov_b32 m0, s40
	s_nop 0
	global_load_lds_dwordx4 v[2:3], off
	s_mov_b32 m0, s8
	s_mov_b64 s[8:9], 0x80
	s_add_i32 s12, s41, 0x8000
	v_lshl_add_u64 v[2:3], v[58:59], 0, s[8:9]
	v_lshl_add_u64 v[4:5], v[60:61], 0, s[8:9]
	s_mov_b32 s8, m0
	s_mov_b32 m0, s12
	s_nop 0
	global_load_lds_dwordx4 v[2:3], off
	s_mov_b32 m0, s8
	s_mov_b64 s[10:11], 0x8080
	v_lshl_add_u64 v[2:3], v[58:59], 0, s[10:11]
	s_add_i32 s13, s41, 0x9000
	s_mov_b32 s8, m0
	s_mov_b32 m0, s13
	s_nop 0
	global_load_lds_dwordx4 v[2:3], off
	s_mov_b32 m0, s8
	s_add_i32 s14, s41, 0xa000
	s_mov_b32 s8, m0
	s_mov_b32 m0, s14
	s_nop 0
	global_load_lds_dwordx4 v[4:5], off
	s_mov_b32 m0, s8
	v_lshl_add_u64 v[2:3], v[60:61], 0, s[10:11]
	s_add_i32 s15, s41, 0xb000
	s_mov_b32 s8, m0
	s_mov_b32 m0, s15
	s_nop 0
	global_load_lds_dwordx4 v[2:3], off
	s_mov_b32 m0, s8
	s_mov_b64 s[10:11], 0xc0
	s_add_i32 s8, s41, 0xc000
	v_lshl_add_u64 v[2:3], v[58:59], 0, s[10:11]
	s_mov_b32 s9, m0
	s_mov_b32 m0, s8
	s_nop 0
	global_load_lds_dwordx4 v[2:3], off
	s_mov_b32 m0, s9
	s_mov_b64 s[48:49], 0x80c0
	v_lshl_add_u64 v[4:5], v[60:61], 0, s[10:11]
	v_lshl_add_u64 v[2:3], v[58:59], 0, s[48:49]
	s_add_i32 s9, s41, 0xd000
	s_mov_b32 s10, m0
	s_mov_b32 m0, s9
	s_nop 0
	global_load_lds_dwordx4 v[2:3], off
	s_mov_b32 m0, s10
	v_lshrrev_b32_e32 v0, 1, v62
	s_add_i32 s10, s41, 0xe000
	s_mov_b32 s11, m0
	s_mov_b32 m0, s10
	s_nop 0
	global_load_lds_dwordx4 v[4:5], off
	s_mov_b32 m0, s11
	v_lshl_add_u64 v[2:3], v[60:61], 0, s[48:49]
	v_and_b32_e32 v0, 6, v0
	v_lshrrev_b32_e32 v6, 4, v62
	s_add_i32 s11, s41, 0xf000
	s_mov_b32 s45, m0
	s_mov_b32 m0, s11
	s_nop 0
	global_load_lds_dwordx4 v[2:3], off
	s_mov_b32 m0, s45
	v_lshrrev_b32_e64 v2, v0, s46
	v_ashrrev_i32_e32 v0, 1, v62
	v_xor_b32_e32 v2, v2, v6
	v_and_b32_e32 v63, 15, v62
	v_and_b32_e32 v0, 0xffffffc0, v0
	v_lshlrev_b32_e32 v2, 4, v2
	v_or_b32_e32 v3, v0, v63
	v_and_b32_e32 v2, 48, v2
	v_lshl_or_b32 v64, v3, 6, v2
	v_lshlrev_b32_e32 v3, 6, v62
	s_movk_i32 s45, 0x13c0
	s_waitcnt vmcnt(12)
	s_barrier
	v_and_or_b32 v65, v3, s45, v2
	ds_read_b128 v[18:21], v64
	ds_read_b128 v[22:25], v65 offset:8192
	s_waitcnt lgkmcnt(2)
	ds_read_b128 v[30:33], v64 offset:1024
	ds_read_b128 v[34:37], v65 offset:9216
	ds_read_b128 v[42:45], v64 offset:2048
	ds_read_b128 v[46:49], v65 offset:10240
	ds_read_b128 v[66:69], v64 offset:3072
	ds_read_b128 v[70:73], v65 offset:11264
	s_waitcnt vmcnt(8)
	s_waitcnt lgkmcnt(0)
	s_barrier
	s_mov_b64 s[46:47], 0x100
	v_lshl_add_u64 v[2:3], v[58:59], 0, s[46:47]
	v_lshl_add_u64 v[4:5], v[60:61], 0, s[46:47]
	s_mov_b32 s45, m0
	s_mov_b32 m0, s41
	s_nop 0
	global_load_lds_dwordx4 v[2:3], off
	s_mov_b32 m0, s45
	s_mov_b64 s[46:47], 0x8100
	v_lshl_add_u64 v[2:3], v[58:59], 0, s[46:47]
	s_mov_b32 s41, m0
	s_mov_b32 m0, s42
	s_nop 0
	global_load_lds_dwordx4 v[2:3], off
	s_mov_b32 m0, s41
	v_lshl_add_u64 v[2:3], v[60:61], 0, s[46:47]
	s_mov_b32 s41, m0
	s_mov_b32 m0, s43
	s_nop 0
	global_load_lds_dwordx4 v[4:5], off
	s_mov_b32 m0, s41
	s_mov_b64 s[42:43], 0x140
	s_mov_b32 s41, m0
	s_mov_b32 m0, s44
	s_nop 0
	global_load_lds_dwordx4 v[2:3], off
	s_mov_b32 m0, s41
	ds_read_b128 v[26:29], v64 offset:16384
	ds_read_b128 v[54:57], v65 offset:24576
	ds_read_b128 v[14:17], v64 offset:17408
	ds_read_b128 v[50:53], v65 offset:25600
	ds_read_b128 v[10:13], v64 offset:18432
	ds_read_b128 v[38:41], v65 offset:26624
	ds_read_b128 v[2:5], v64 offset:19456
	ds_read_b128 v[6:9], v65 offset:27648
	s_waitcnt vmcnt(8)
	s_waitcnt lgkmcnt(0)
	s_barrier
;     ...
;   asm volatile("s_waitcnt vmcnt(12)" ::: "memory");
;   __builtin_amdgcn_s_barrier();
;   asm volatile("" ::: "memory");
;   GEMM_READ(0, xa0, wb0);
;   for (int kt = 0; kt < nk; kt += 2) {
;     GEMM_STEP(kt, xa0, wb0, xa1, wb1);
;     GEMM_STEP(kt + 1, xa1, wb1, xa0, wb0);
;   }
	s_waitcnt lgkmcnt(14)
	v_mfma_f32_16x16x32_bf16 v[74:77], v[22:25], v[18:21], 0
	s_waitcnt lgkmcnt(12)
	v_mfma_f32_16x16x32_bf16 v[90:93], v[34:37], v[18:21], 0
	s_waitcnt lgkmcnt(10)
	v_mfma_f32_16x16x32_bf16 v[106:109], v[46:49], v[18:21], 0
	s_waitcnt lgkmcnt(8)
	v_mfma_f32_16x16x32_bf16 v[122:125], v[70:73], v[18:21], 0
	v_lshl_add_u64 v[18:19], v[58:59], 0, s[42:43]
	v_lshl_add_u64 v[20:21], v[60:61], 0, s[42:43]
	s_mov_b32 s41, m0
	s_mov_b32 m0, s36
	s_nop 0
	global_load_lds_dwordx4 v[18:19], off
	s_mov_b32 m0, s41
	s_mov_b64 s[42:43], 0x8140
	v_lshl_add_u64 v[18:19], v[58:59], 0, s[42:43]
	s_mov_b32 s36, m0
	s_mov_b32 m0, s37
	s_nop 0
	global_load_lds_dwordx4 v[18:19], off
	s_mov_b32 m0, s36
	v_mfma_f32_16x16x32_bf16 v[78:81], v[22:25], v[30:33], 0
	s_mov_b32 s36, m0
	s_mov_b32 m0, s39
	s_nop 0
	global_load_lds_dwordx4 v[20:21], off
	s_mov_b32 m0, s36
	v_lshl_add_u64 v[18:19], v[60:61], 0, s[42:43]
	s_mov_b32 s36, m0
	s_mov_b32 m0, s40
	s_nop 0
	global_load_lds_dwordx4 v[18:19], off
	s_mov_b32 m0, s36
	v_mfma_f32_16x16x32_bf16 v[82:85], v[22:25], v[42:45], 0
	s_mov_b64 s[36:37], 0x180
	v_mfma_f32_16x16x32_bf16 v[86:89], v[22:25], v[66:69], 0
	v_mfma_f32_16x16x32_bf16 v[94:97], v[34:37], v[30:33], 0
	v_mfma_f32_16x16x32_bf16 v[98:101], v[34:37], v[42:45], 0
	v_mfma_f32_16x16x32_bf16 v[102:105], v[34:37], v[66:69], 0
	v_mfma_f32_16x16x32_bf16 v[110:113], v[46:49], v[30:33], 0
	v_mfma_f32_16x16x32_bf16 v[118:121], v[46:49], v[66:69], 0
	v_mfma_f32_16x16x32_bf16 v[66:69], v[70:73], v[66:69], 0
	v_mfma_f32_16x16x32_bf16 v[114:117], v[46:49], v[42:45], 0
	v_mfma_f32_16x16x32_bf16 v[126:129], v[70:73], v[30:33], 0
	v_mfma_f32_16x16x32_bf16 v[132:135], v[70:73], v[42:45], 0
	ds_read_b128 v[42:45], v64 offset:32768
	ds_read_b128 v[70:73], v65 offset:40960
	ds_read_b128 v[34:37], v64 offset:33792
	ds_read_b128 v[136:139], v65 offset:41984
	ds_read_b128 v[30:33], v64 offset:34816
	ds_read_b128 v[46:49], v65 offset:43008
	ds_read_b128 v[18:21], v64 offset:35840
	ds_read_b128 v[22:25], v65 offset:44032
	s_waitcnt vmcnt(8)
	s_waitcnt lgkmcnt(0)
	s_barrier
	s_waitcnt lgkmcnt(14)
	v_mfma_f32_16x16x32_bf16 v[74:77], v[54:57], v[26:29], v[74:77]
	s_waitcnt lgkmcnt(13)
	v_mfma_f32_16x16x32_bf16 v[78:81], v[54:57], v[14:17], v[78:81]
	s_waitcnt lgkmcnt(11)
	v_mfma_f32_16x16x32_bf16 v[82:85], v[54:57], v[10:13], v[82:85]
	s_waitcnt lgkmcnt(9)
	v_mfma_f32_16x16x32_bf16 v[54:57], v[54:57], v[2:5], v[86:89]
	v_mfma_f32_16x16x32_bf16 v[86:89], v[50:53], v[26:29], v[90:93]
	v_mfma_f32_16x16x32_bf16 v[90:93], v[50:53], v[14:17], v[94:97]
	v_mfma_f32_16x16x32_bf16 v[94:97], v[50:53], v[10:13], v[98:101]
	v_mfma_f32_16x16x32_bf16 v[50:53], v[50:53], v[2:5], v[102:105]
	v_mfma_f32_16x16x32_bf16 v[102:105], v[38:41], v[14:17], v[110:113]
	v_mfma_f32_16x16x32_bf16 v[110:113], v[38:41], v[2:5], v[118:121]
	s_waitcnt lgkmcnt(8)
	v_mfma_f32_16x16x32_bf16 v[66:69], v[6:9], v[2:5], v[66:69]
	v_lshl_add_u64 v[2:3], v[58:59], 0, s[36:37]
	v_lshl_add_u64 v[4:5], v[60:61], 0, s[36:37]
	s_mov_b32 s36, m0
	s_mov_b32 m0, s12
	s_nop 0
	global_load_lds_dwordx4 v[2:3], off
	s_mov_b32 m0, s36
	s_mov_b64 s[36:37], 0x8180
	v_lshl_add_u64 v[2:3], v[58:59], 0, s[36:37]
	s_mov_b32 s12, m0
	s_mov_b32 m0, s13
	s_nop 0
	global_load_lds_dwordx4 v[2:3], off
	s_mov_b32 m0, s12
	v_mfma_f32_16x16x32_bf16 v[98:101], v[38:41], v[26:29], v[106:109]
	s_mov_b32 s12, m0
	s_mov_b32 m0, s14
	s_nop 0
	global_load_lds_dwordx4 v[4:5], off
	s_mov_b32 m0, s12
	v_lshl_add_u64 v[2:3], v[60:61], 0, s[36:37]
	s_mov_b32 s12, m0
	s_mov_b32 m0, s15
	s_nop 0
	global_load_lds_dwordx4 v[2:3], off
	s_mov_b32 m0, s12
	v_mfma_f32_16x16x32_bf16 v[106:109], v[38:41], v[10:13], v[114:117]
	s_mov_b64 s[12:13], 0x1c0
	v_mfma_f32_16x16x32_bf16 v[114:117], v[6:9], v[26:29], v[122:125]
	v_mfma_f32_16x16x32_bf16 v[118:121], v[6:9], v[14:17], v[126:129]
	v_mfma_f32_16x16x32_bf16 v[122:125], v[6:9], v[10:13], v[132:135]
	ds_read_b128 v[26:29], v64 offset:49152
	s_nop 0
	ds_read_b128 v[126:129], v65 offset:57344
	ds_read_b128 v[14:17], v64 offset:50176
	ds_read_b128 v[132:135], v65 offset:58368
	ds_read_b128 v[10:13], v64 offset:51200
	ds_read_b128 v[38:41], v65 offset:59392
	ds_read_b128 v[2:5], v64 offset:52224
	ds_read_b128 v[6:9], v65 offset:60416
	s_waitcnt vmcnt(8)
	s_waitcnt lgkmcnt(0)
	s_barrier
	s_waitcnt lgkmcnt(14)
	v_mfma_f32_16x16x32_bf16 v[74:77], v[70:73], v[42:45], v[74:77]
	s_waitcnt lgkmcnt(13)
	v_mfma_f32_16x16x32_bf16 v[78:81], v[70:73], v[34:37], v[78:81]
	s_waitcnt lgkmcnt(11)
	v_mfma_f32_16x16x32_bf16 v[82:85], v[70:73], v[30:33], v[82:85]
	s_waitcnt lgkmcnt(9)
	v_mfma_f32_16x16x32_bf16 v[54:57], v[70:73], v[18:21], v[54:57]
	v_mfma_f32_16x16x32_bf16 v[70:73], v[136:139], v[42:45], v[86:89]
	v_mfma_f32_16x16x32_bf16 v[86:89], v[136:139], v[34:37], v[90:93]
	v_mfma_f32_16x16x32_bf16 v[90:93], v[136:139], v[30:33], v[94:97]
	v_mfma_f32_16x16x32_bf16 v[50:53], v[136:139], v[18:21], v[50:53]
	v_mfma_f32_16x16x32_bf16 v[94:97], v[46:49], v[42:45], v[98:101]
	v_mfma_f32_16x16x32_bf16 v[98:101], v[46:49], v[34:37], v[102:105]
	v_mfma_f32_16x16x32_bf16 v[102:105], v[46:49], v[30:33], v[106:109]
	v_mfma_f32_16x16x32_bf16 v[46:49], v[46:49], v[18:21], v[110:113]
	s_waitcnt lgkmcnt(8)
	v_mfma_f32_16x16x32_bf16 v[42:45], v[22:25], v[42:45], v[114:117]
	v_mfma_f32_16x16x32_bf16 v[34:37], v[22:25], v[34:37], v[118:121]
	v_mfma_f32_16x16x32_bf16 v[30:33], v[22:25], v[30:33], v[122:125]
	v_mfma_f32_16x16x32_bf16 v[18:21], v[22:25], v[18:21], v[66:69]
	v_lshl_add_u64 v[22:23], v[58:59], 0, s[12:13]
	v_lshl_add_u64 v[24:25], v[60:61], 0, s[12:13]
	s_mov_b32 s12, m0
	s_mov_b32 m0, s8
	s_nop 0
	global_load_lds_dwordx4 v[22:23], off
	s_mov_b32 m0, s12
	s_mov_b64 s[12:13], 0x81c0
	v_lshl_add_u64 v[22:23], v[58:59], 0, s[12:13]
	s_mov_b32 s8, m0
	s_mov_b32 m0, s9
	s_nop 0
	global_load_lds_dwordx4 v[22:23], off
	s_mov_b32 m0, s8
	v_lshl_add_u64 v[22:23], v[60:61], 0, s[12:13]
	s_mov_b32 s8, m0
	s_mov_b32 m0, s10
	s_nop 0
	global_load_lds_dwordx4 v[24:25], off
	s_mov_b32 m0, s8
	s_waitcnt lgkmcnt(6)
	v_mfma_f32_16x16x32_bf16 v[74:77], v[126:129], v[26:29], v[74:77]
	s_mov_b32 s8, m0
	s_mov_b32 m0, s11
	s_nop 0
	global_load_lds_dwordx4 v[22:23], off
	s_mov_b32 m0, s8
	ds_read_b128 v[22:25], v64
	ds_read_b128 v[58:61], v65 offset:8192
	ds_read_b128 v[66:69], v64 offset:1024
	ds_read_b128 v[106:109], v65 offset:9216
	ds_read_b128 v[110:113], v64 offset:2048
	ds_read_b128 v[114:117], v65 offset:10240
	ds_read_b128 v[118:121], v64 offset:3072
	ds_read_b128 v[122:125], v65 offset:11264
	s_waitcnt vmcnt(8)
	s_waitcnt lgkmcnt(13)
	v_mfma_f32_16x16x32_bf16 v[78:81], v[126:129], v[14:17], v[78:81]
	s_waitcnt lgkmcnt(0)
	s_barrier
; DEVI int xcd_first_tile() { return (blockIdx.x & 7) * (gridDim.x >> 3) + (blockIdx.x >> 3); }
;     ...
;   asm volatile("s_waitcnt vmcnt(12)" ::: "memory");
;   __builtin_amdgcn_s_barrier();
;   asm volatile("" ::: "memory");
;   GEMM_READ(0, xa0, wb0);
;   for (int kt = 0; kt < nk; kt += 2) {
;     GEMM_STEP(kt, xa0, wb0, xa1, wb1);
;     GEMM_STEP(kt + 1, xa1, wb1, xa0, wb0);
;   }
; DEVI void run_phase(const Params& p, int ph, char* smem) {
;     ...
;       for (int t = xcd_first_tile(); t < 132 * 2; t += xcd_tile_step()) {
	s_waitcnt lgkmcnt(11)
	v_mfma_f32_16x16x32_bf16 v[82:85], v[126:129], v[10:13], v[82:85]
	v_readlane_b32 s8, v250, 1
	v_readlane_b32 s12, v250, 5
	v_readlane_b32 s13, v250, 6
	s_waitcnt lgkmcnt(9)
	v_mfma_f32_16x16x32_bf16 v[54:57], v[126:129], v[2:5], v[54:57]
	v_readlane_b32 s14, v250, 7
	s_add_i32 s0, s0, s14
	s_cmpk_gt_i32 s0, 0x107
	v_mfma_f32_16x16x32_bf16 v[70:73], v[132:135], v[26:29], v[70:73]
	v_readlane_b32 s9, v250, 2
	v_readlane_b32 s10, v250, 3
	v_readlane_b32 s11, v250, 4
	v_mfma_f32_16x16x32_bf16 v[86:89], v[132:135], v[14:17], v[86:89]
	v_readlane_b32 s15, v250, 8
	v_mfma_f32_16x16x32_bf16 v[90:93], v[132:135], v[10:13], v[90:93]
	v_mfma_f32_16x16x32_bf16 v[50:53], v[132:135], v[2:5], v[50:53]
	v_mfma_f32_16x16x32_bf16 v[94:97], v[38:41], v[26:29], v[94:97]
	v_mfma_f32_16x16x32_bf16 v[98:101], v[38:41], v[14:17], v[98:101]
	v_mfma_f32_16x16x32_bf16 v[102:105], v[38:41], v[10:13], v[102:105]
	v_mfma_f32_16x16x32_bf16 v[38:41], v[38:41], v[2:5], v[46:49]
	s_waitcnt lgkmcnt(8)
	v_mfma_f32_16x16x32_bf16 v[26:29], v[6:9], v[26:29], v[42:45]
	v_mfma_f32_16x16x32_bf16 v[14:17], v[6:9], v[14:17], v[34:37]
	v_mfma_f32_16x16x32_bf16 v[10:13], v[6:9], v[10:13], v[30:33]
	v_mfma_f32_16x16x32_bf16 v[2:5], v[6:9], v[2:5], v[18:21]
	ds_read_b128 v[6:9], v64 offset:16384
	s_nop 1
	ds_read_b128 v[18:21], v65 offset:24576
	ds_read_b128 v[30:33], v64 offset:17408
	ds_read_b128 v[34:37], v65 offset:25600
	ds_read_b128 v[42:45], v64 offset:18432
	ds_read_b128 v[46:49], v65 offset:26624
	ds_read_b128 v[126:129], v64 offset:19456
	ds_read_b128 v[132:135], v65 offset:27648
	s_waitcnt vmcnt(4)
	s_waitcnt lgkmcnt(0)
	s_waitcnt lgkmcnt(14)
	v_mfma_f32_16x16x32_bf16 v[74:77], v[58:61], v[22:25], v[74:77]
	s_barrier
	s_waitcnt lgkmcnt(13)
	v_mfma_f32_16x16x32_bf16 v[78:81], v[58:61], v[66:69], v[78:81]
	s_waitcnt lgkmcnt(11)
	v_mfma_f32_16x16x32_bf16 v[82:85], v[58:61], v[110:113], v[82:85]
	s_waitcnt lgkmcnt(9)
	v_mfma_f32_16x16x32_bf16 v[54:57], v[58:61], v[118:121], v[54:57]
	v_mfma_f32_16x16x32_bf16 v[58:61], v[106:109], v[22:25], v[70:73]
	v_mfma_f32_16x16x32_bf16 v[70:73], v[106:109], v[66:69], v[86:89]
	v_mfma_f32_16x16x32_bf16 v[86:89], v[106:109], v[110:113], v[90:93]
	v_mfma_f32_16x16x32_bf16 v[50:53], v[106:109], v[118:121], v[50:53]
	v_mfma_f32_16x16x32_bf16 v[90:93], v[114:117], v[22:25], v[94:97]
	v_mfma_f32_16x16x32_bf16 v[94:97], v[114:117], v[66:69], v[98:101]
	s_waitcnt lgkmcnt(8)
	v_mfma_f32_16x16x32_bf16 v[14:17], v[122:125], v[66:69], v[14:17]
	s_waitcnt lgkmcnt(6)
	v_mfma_f32_16x16x32_bf16 v[74:77], v[18:21], v[6:9], v[74:77]
	s_waitcnt lgkmcnt(5)
	v_mfma_f32_16x16x32_bf16 v[78:81], v[18:21], v[30:33], v[78:81]
	s_waitcnt lgkmcnt(3)
	v_mfma_f32_16x16x32_bf16 v[82:85], v[18:21], v[42:45], v[82:85]
	s_waitcnt lgkmcnt(1)
	v_mfma_f32_16x16x32_bf16 v[18:21], v[18:21], v[126:129], v[54:57]
	v_mfma_f32_16x16x32_bf16 v[54:57], v[34:37], v[6:9], v[58:61]
	v_mfma_f32_16x16x32_bf16 v[98:101], v[114:117], v[110:113], v[102:105]
	v_mfma_f32_16x16x32_bf16 v[38:41], v[114:117], v[118:121], v[38:41]
	v_mfma_f32_16x16x32_bf16 v[22:25], v[122:125], v[22:25], v[26:29]
	v_mfma_f32_16x16x32_bf16 v[10:13], v[122:125], v[110:113], v[10:13]
	v_mfma_f32_16x16x32_bf16 v[2:5], v[122:125], v[118:121], v[2:5]
	s_nop 0
	ds_read_b128 v[26:29], v64 offset:32768
	ds_read_b128 v[66:69], v65 offset:40960
	ds_read_b128 v[102:105], v64 offset:33792
	ds_read_b128 v[106:109], v65 offset:41984
	ds_read_b128 v[110:113], v64 offset:34816
	ds_read_b128 v[114:117], v65 offset:43008
	ds_read_b128 v[118:121], v64 offset:35840
	ds_read_b128 v[122:125], v65 offset:44032
	s_waitcnt vmcnt(0)
	s_waitcnt lgkmcnt(0)
	v_mfma_f32_16x16x32_bf16 v[58:61], v[34:37], v[30:33], v[70:73]
	s_barrier
	v_mfma_f32_16x16x32_bf16 v[70:73], v[34:37], v[42:45], v[86:89]
	v_mfma_f32_16x16x32_bf16 v[34:37], v[34:37], v[126:129], v[50:53]
	v_mfma_f32_16x16x32_bf16 v[86:89], v[46:49], v[30:33], v[94:97]
	s_waitcnt lgkmcnt(8)
	v_mfma_f32_16x16x32_bf16 v[14:17], v[132:135], v[30:33], v[14:17]
	s_waitcnt lgkmcnt(6)
	v_mfma_f32_16x16x32_bf16 v[30:33], v[66:69], v[26:29], v[74:77]
	s_waitcnt lgkmcnt(3)
	v_mfma_f32_16x16x32_bf16 v[74:77], v[66:69], v[110:113], v[82:85]
	v_mfma_f32_16x16x32_bf16 v[54:57], v[106:109], v[26:29], v[54:57]
	v_mfma_f32_16x16x32_bf16 v[50:53], v[46:49], v[6:9], v[90:93]
	v_mfma_f32_16x16x32_bf16 v[90:93], v[46:49], v[42:45], v[98:101]
	v_mfma_f32_16x16x32_bf16 v[38:41], v[46:49], v[126:129], v[38:41]
	v_mfma_f32_16x16x32_bf16 v[6:9], v[132:135], v[6:9], v[22:25]
	v_mfma_f32_16x16x32_bf16 v[10:13], v[132:135], v[42:45], v[10:13]
	v_mfma_f32_16x16x32_bf16 v[2:5], v[132:135], v[126:129], v[2:5]
	ds_read_b128 v[94:97], v64 offset:49152
	ds_read_b128 v[22:25], v65 offset:57344
	ds_read_b128 v[98:101], v64 offset:50176
	ds_read_b128 v[126:129], v65 offset:58368
	ds_read_b128 v[132:135], v64 offset:51200
	ds_read_b128 v[136:139], v65 offset:59392
	ds_read_b128 v[140:143], v64 offset:52224
	ds_read_b128 v[146:149], v65 offset:60416
	s_waitcnt vmcnt(0)
	s_waitcnt lgkmcnt(0)
	v_mfma_f32_16x16x32_bf16 v[42:45], v[66:69], v[102:105], v[78:81]
	s_barrier
; DEVI unsigned pack2(float a, float b) { return __builtin_bit_cast(unsigned, __builtin_convertvector((f32x2_t){a, b}, bf16x2_t)); }
;     ...
;         } else if (EPI == EPI_POOL) {
;           const float4 sc = *(const float4*)(p.pool_scale + l * 256 + col);
;           uint2 pk; pk.x = pack2(a[0] * sc.x, a[1] * sc.y); pk.y = pack2(a[2] * sc.z, a[3] * sc.w);
;           *(uint2*)((u16*)(p.ws + WS_MIX) + (size_t)row * 1024 + 768 + col) = pk;
;         }
	s_waitcnt lgkmcnt(9)
	v_mfma_f32_16x16x32_bf16 v[18:21], v[66:69], v[118:121], v[18:21]
	v_mfma_f32_16x16x32_bf16 v[58:61], v[106:109], v[102:105], v[58:61]
	v_mfma_f32_16x16x32_bf16 v[64:67], v[106:109], v[110:113], v[70:73]
	v_mfma_f32_16x16x32_bf16 v[34:37], v[106:109], v[118:121], v[34:37]
	s_waitcnt lgkmcnt(6)
	v_mfma_f32_16x16x32_bf16 v[106:109], v[22:25], v[94:97], v[30:33]
	s_waitcnt lgkmcnt(3)
	v_mfma_f32_16x16x32_bf16 v[30:33], v[22:25], v[132:135], v[74:77]
	v_mfma_f32_16x16x32_bf16 v[72:75], v[126:129], v[94:97], v[54:57]
	s_nop 2
	v_or_b32_e32 v55, s3, v63
	v_add_u32_e32 v56, v55, v0
	v_lshrrev_b32_e32 v0, 2, v62
	v_and_b32_e32 v54, 64, v62
	v_and_b32_e32 v0, 12, v0
	v_or3_b32 v76, v54, v0, s2
	v_ashrrev_i32_e32 v77, 31, v76
	v_lshl_add_u64 v[54:55], v[76:77], 2, s[6:7]
	v_mfma_f32_16x16x32_bf16 v[46:49], v[22:25], v[98:101], v[42:45]
	v_ashrrev_i32_e32 v57, 31, v56
	v_lshlrev_b64 v[62:63], 11, v[56:57]
	s_mov_b64 s[2:3], 0xb580600
	v_mfma_f32_16x16x32_bf16 v[42:45], v[126:129], v[98:101], v[58:61]
	s_nop 2
	global_load_dwordx4 v[176:179], v[54:55], off
	global_load_dwordx4 v[180:183], v[54:55], off offset:64
	global_load_dwordx4 v[184:187], v[54:55], off offset:128
	global_load_dwordx4 v[188:191], v[54:55], off offset:192
	s_waitcnt vmcnt(0)
	s_nop 2
	v_mov_b32_e32 v58, v176
	v_mov_b32_e32 v59, v177
	v_mov_b32_e32 v60, v178
	v_mov_b32_e32 v61, v179
	v_mfma_f32_16x16x32_bf16 v[68:71], v[114:117], v[102:105], v[86:89]
	v_pk_mul_f32 v[58:59], v[106:107], v[58:59]
	v_mfma_f32_16x16x32_bf16 v[78:81], v[114:117], v[110:113], v[90:93]
	v_mfma_f32_16x16x32_bf16 v[82:85], v[114:117], v[118:121], v[38:41]
	s_waitcnt lgkmcnt(2)
	v_mfma_f32_16x16x32_bf16 v[38:41], v[136:139], v[98:101], v[68:71]
	s_nop 2
	v_cvt_pk_bf16_f32 v68, v58, v59
	v_pk_mul_f32 v[58:59], v[108:109], v[60:61]
	v_mfma_f32_16x16x32_bf16 v[90:93], v[122:125], v[102:105], v[14:17]
	v_cvt_pk_bf16_f32 v69, v58, v59
	v_lshl_add_u64 v[58:59], s[12:13], 0, v[62:63]
	s_waitcnt lgkmcnt(1)
	v_mfma_f32_16x16x32_bf16 v[14:17], v[22:25], v[140:143], v[18:21]
	v_mfma_f32_16x16x32_bf16 v[22:25], v[136:139], v[132:135], v[78:81]
	s_nop 2
	v_lshl_add_u64 v[78:79], v[58:59], 0, s[2:3]
	v_lshlrev_b64 v[58:59], 1, v[76:77]
	v_lshl_add_u64 v[60:61], v[78:79], 0, v[58:59]
	global_store_dwordx2 v[60:61], v[68:69], off
	v_mov_b32_e32 v60, v180
	v_mov_b32_e32 v61, v181
	v_mov_b32_e32 v62, v182
	v_mov_b32_e32 v63, v183
	v_or_b32_e32 v68, 16, v76
	v_ashrrev_i32_e32 v69, 31, v68
	v_mfma_f32_16x16x32_bf16 v[50:53], v[114:117], v[26:29], v[50:53]
	v_pk_mul_f32 v[60:61], v[72:73], v[60:61]
	s_nop 0
	v_cvt_pk_bf16_f32 v70, v60, v61
	v_pk_mul_f32 v[60:61], v[74:75], v[62:63]
	v_mfma_f32_16x16x32_bf16 v[86:89], v[122:125], v[26:29], v[6:9]
	v_cvt_pk_bf16_f32 v71, v60, v61
	v_lshlrev_b64 v[60:61], 1, v[68:69]
	v_lshl_add_u64 v[62:63], v[78:79], 0, v[60:61]
	global_store_dwordx2 v[62:63], v[70:71], off
	v_mov_b32_e32 v68, v184
	v_mov_b32_e32 v69, v185
	v_mov_b32_e32 v70, v186
	v_mov_b32_e32 v71, v187
	v_mfma_f32_16x16x32_bf16 v[26:29], v[126:129], v[132:135], v[64:67]
	v_or_b32_e32 v62, 32, v76
	v_ashrrev_i32_e32 v63, 31, v62
	v_lshlrev_b64 v[62:63], 1, v[62:63]
	v_mfma_f32_16x16x32_bf16 v[64:67], v[136:139], v[94:97], v[50:53]
	s_waitcnt lgkmcnt(0)
; DEVI unsigned pack2(float a, float b) { return __builtin_bit_cast(unsigned, __builtin_convertvector((f32x2_t){a, b}, bf16x2_t)); }
;     ...
;         } else if (EPI == EPI_POOL) {
;           const float4 sc = *(const float4*)(p.pool_scale + l * 256 + col);
;           uint2 pk; pk.x = pack2(a[0] * sc.x, a[1] * sc.y); pk.y = pack2(a[2] * sc.z, a[3] * sc.w);
;           *(uint2*)((u16*)(p.ws + WS_MIX) + (size_t)row * 1024 + 768 + col) = pk;
;         }
	v_mfma_f32_16x16x32_bf16 v[50:53], v[146:149], v[94:97], v[86:89]
	v_mfma_f32_16x16x32_bf16 v[102:105], v[122:125], v[110:113], v[10:13]
	s_nop 3
	v_pk_mul_f32 v[64:65], v[64:65], v[68:69]
	v_pk_mul_f32 v[66:67], v[66:67], v[70:71]
	v_cvt_pk_bf16_f32 v64, v64, v65
	v_cvt_pk_bf16_f32 v65, v66, v67
	v_lshl_add_u64 v[66:67], v[78:79], 0, v[62:63]
	global_store_dwordx2 v[66:67], v[64:65], off
	v_mov_b32_e32 v64, v188
	v_mov_b32_e32 v65, v189
	v_mov_b32_e32 v66, v190
	v_mov_b32_e32 v67, v191
	v_or_b32_e32 v68, 48, v76
	v_ashrrev_i32_e32 v69, 31, v68
	v_mfma_f32_16x16x32_bf16 v[10:13], v[126:129], v[140:143], v[34:37]
	v_pk_mul_f32 v[50:51], v[50:51], v[64:65]
	s_nop 0
	v_cvt_pk_bf16_f32 v64, v50, v51
	v_pk_mul_f32 v[50:51], v[52:53], v[66:67]
	v_mfma_f32_16x16x32_bf16 v[34:37], v[146:149], v[98:101], v[90:93]
	v_cvt_pk_bf16_f32 v65, v50, v51
	v_lshlrev_b64 v[50:51], 1, v[68:69]
	v_lshl_add_u64 v[52:53], v[78:79], 0, v[50:51]
	global_store_dwordx2 v[52:53], v[64:65], off
	v_mov_b32_e32 v64, v176
	v_mov_b32_e32 v65, v177
	v_mov_b32_e32 v66, v178
	v_mov_b32_e32 v67, v179
	v_or_b32_e32 v52, 16, v56
	v_ashrrev_i32_e32 v53, 31, v52
	v_lshlrev_b64 v[52:53], 11, v[52:53]
	v_mfma_f32_16x16x32_bf16 v[18:21], v[146:149], v[132:135], v[102:105]
	v_pk_mul_f32 v[46:47], v[46:47], v[64:65]
	v_pk_mul_f32 v[48:49], v[48:49], v[66:67]
	v_cvt_pk_bf16_f32 v46, v46, v47
	v_cvt_pk_bf16_f32 v47, v48, v49
	v_lshl_add_u64 v[48:49], s[12:13], 0, v[52:53]
	v_lshl_add_u64 v[52:53], v[48:49], 0, s[2:3]
	v_lshl_add_u64 v[48:49], v[52:53], 0, v[58:59]
	global_store_dwordx2 v[48:49], v[46:47], off
	v_mov_b32_e32 v46, v180
	v_mov_b32_e32 v47, v181
	v_mov_b32_e32 v48, v182
	v_mov_b32_e32 v49, v183
	v_mfma_f32_16x16x32_bf16 v[6:9], v[136:139], v[140:143], v[82:85]
	v_pk_mul_f32 v[42:43], v[42:43], v[46:47]
	v_pk_mul_f32 v[44:45], v[44:45], v[48:49]
	v_cvt_pk_bf16_f32 v42, v42, v43
	v_cvt_pk_bf16_f32 v43, v44, v45
	v_lshl_add_u64 v[44:45], v[52:53], 0, v[60:61]
	global_store_dwordx2 v[44:45], v[42:43], off
	v_mov_b32_e32 v42, v184
	v_mov_b32_e32 v43, v185
	v_mov_b32_e32 v44, v186
	v_mov_b32_e32 v45, v187
	v_mfma_f32_16x16x32_bf16 v[2:5], v[122:125], v[118:121], v[2:5]
	v_pk_mul_f32 v[38:39], v[38:39], v[42:43]
	v_pk_mul_f32 v[40:41], v[40:41], v[44:45]
	v_cvt_pk_bf16_f32 v38, v38, v39
	v_cvt_pk_bf16_f32 v39, v40, v41
	v_lshl_add_u64 v[40:41], v[52:53], 0, v[62:63]
	global_store_dwordx2 v[40:41], v[38:39], off
	v_mov_b32_e32 v38, v188
	v_mov_b32_e32 v39, v189
	v_mov_b32_e32 v40, v190
	v_mov_b32_e32 v41, v191
	v_mfma_f32_16x16x32_bf16 v[2:5], v[146:149], v[140:143], v[2:5]
	v_pk_mul_f32 v[34:35], v[34:35], v[38:39]
	v_pk_mul_f32 v[36:37], v[36:37], v[40:41]
	v_cvt_pk_bf16_f32 v34, v34, v35
	v_cvt_pk_bf16_f32 v35, v36, v37
	v_lshl_add_u64 v[36:37], v[52:53], 0, v[50:51]
	global_store_dwordx2 v[36:37], v[34:35], off
	v_or_b32_e32 v34, 32, v56
	v_ashrrev_i32_e32 v35, 31, v34
	v_lshlrev_b64 v[38:39], 11, v[34:35]
	v_mov_b32_e32 v34, v176
	v_mov_b32_e32 v35, v177
	v_mov_b32_e32 v36, v178
	v_mov_b32_e32 v37, v179
	v_pk_mul_f32 v[30:31], v[30:31], v[34:35]
	v_pk_mul_f32 v[32:33], v[32:33], v[36:37]
	v_cvt_pk_bf16_f32 v30, v30, v31
	v_cvt_pk_bf16_f32 v31, v32, v33
	v_lshl_add_u64 v[32:33], s[12:13], 0, v[38:39]
	v_lshl_add_u64 v[34:35], v[32:33], 0, s[2:3]
	v_lshl_add_u64 v[32:33], v[34:35], 0, v[58:59]
	global_store_dwordx2 v[32:33], v[30:31], off
	v_mov_b32_e32 v30, v180
	v_mov_b32_e32 v31, v181
	v_mov_b32_e32 v32, v182
	v_mov_b32_e32 v33, v183
	v_pk_mul_f32 v[26:27], v[26:27], v[30:31]
	v_pk_mul_f32 v[28:29], v[28:29], v[32:33]
	v_cvt_pk_bf16_f32 v26, v26, v27
	v_cvt_pk_bf16_f32 v27, v28, v29
	v_lshl_add_u64 v[28:29], v[34:35], 0, v[60:61]
	global_store_dwordx2 v[28:29], v[26:27], off
	v_mov_b32_e32 v26, v184
	v_mov_b32_e32 v27, v185
	v_mov_b32_e32 v28, v186
	v_mov_b32_e32 v29, v187
	v_pk_mul_f32 v[22:23], v[22:23], v[26:27]
	v_pk_mul_f32 v[24:25], v[24:25], v[28:29]
	v_cvt_pk_bf16_f32 v22, v22, v23
	v_cvt_pk_bf16_f32 v23, v24, v25
	v_lshl_add_u64 v[24:25], v[34:35], 0, v[62:63]
	global_store_dwordx2 v[24:25], v[22:23], off
	v_mov_b32_e32 v22, v188
	v_mov_b32_e32 v23, v189
	v_mov_b32_e32 v24, v190
	v_mov_b32_e32 v25, v191
	v_pk_mul_f32 v[18:19], v[18:19], v[22:23]
	v_pk_mul_f32 v[20:21], v[20:21], v[24:25]
	v_cvt_pk_bf16_f32 v18, v18, v19
	v_cvt_pk_bf16_f32 v19, v20, v21
	v_lshl_add_u64 v[20:21], v[34:35], 0, v[50:51]
	global_store_dwordx2 v[20:21], v[18:19], off
	v_or_b32_e32 v18, 48, v56
	v_ashrrev_i32_e32 v19, 31, v18
	v_lshlrev_b64 v[22:23], 11, v[18:19]
	v_mov_b32_e32 v18, v176
	v_mov_b32_e32 v19, v177
	v_mov_b32_e32 v20, v178
	v_mov_b32_e32 v21, v179
	v_pk_mul_f32 v[14:15], v[14:15], v[18:19]
	v_pk_mul_f32 v[16:17], v[16:17], v[20:21]
	v_cvt_pk_bf16_f32 v14, v14, v15
	v_cvt_pk_bf16_f32 v15, v16, v17
	v_lshl_add_u64 v[16:17], s[12:13], 0, v[22:23]
	v_lshl_add_u64 v[18:19], v[16:17], 0, s[2:3]
	v_lshl_add_u64 v[16:17], v[18:19], 0, v[58:59]
	global_store_dwordx2 v[16:17], v[14:15], off
	v_mov_b32_e32 v14, v180
	v_mov_b32_e32 v15, v181
	v_mov_b32_e32 v16, v182
	v_mov_b32_e32 v17, v183
	v_pk_mul_f32 v[10:11], v[10:11], v[14:15]
	v_pk_mul_f32 v[12:13], v[12:13], v[16:17]
	v_cvt_pk_bf16_f32 v10, v10, v11
	v_cvt_pk_bf16_f32 v11, v12, v13
	v_lshl_add_u64 v[12:13], v[18:19], 0, v[60:61]
	global_store_dwordx2 v[12:13], v[10:11], off
	v_mov_b32_e32 v10, v184
	v_mov_b32_e32 v11, v185
	v_mov_b32_e32 v12, v186
	v_mov_b32_e32 v13, v187
	v_pk_mul_f32 v[6:7], v[6:7], v[10:11]
	v_pk_mul_f32 v[8:9], v[8:9], v[12:13]
	v_cvt_pk_bf16_f32 v6, v6, v7
	v_cvt_pk_bf16_f32 v7, v8, v9
	v_lshl_add_u64 v[8:9], v[18:19], 0, v[62:63]
	global_store_dwordx2 v[8:9], v[6:7], off
	v_mov_b32_e32 v6, v188
	v_mov_b32_e32 v7, v189
	v_mov_b32_e32 v8, v190
	v_mov_b32_e32 v9, v191
	v_pk_mul_f32 v[2:3], v[2:3], v[6:7]
	v_pk_mul_f32 v[4:5], v[4:5], v[8:9]
	v_cvt_pk_bf16_f32 v2, v2, v3
	v_cvt_pk_bf16_f32 v3, v4, v5
	v_lshl_add_u64 v[4:5], v[18:19], 0, v[50:51]
	global_store_dwordx2 v[4:5], v[2:3], off
	s_cbranch_scc1 .LBB0_881
